# attention rescale o*=alpha via v_pk_mul_f32 (32 packed instead of 64 single muls per K-tile) in all 6 attention loops
# baseline (speedup 1.0000x reference)
.LBB0_323:
	s_and_saveexec_b64 s[72:73], s[6:7]
	s_cbranch_execz .LBB0_310
	ds_read_b128 v[220:223], v245
	ds_read_b128 v[224:227], v245 offset:32
	ds_read_b128 v[2:5], v245 offset:64
	ds_read_b128 v[6:9], v245 offset:96
	s_waitcnt lgkmcnt(3)
	v_mfma_f32_32x32x16_bf16 v[96:111], v[220:223], v[172:175], 0
	ds_read_b128 v[220:223], v245 offset:128
	s_waitcnt lgkmcnt(3)
	v_mfma_f32_32x32x16_bf16 v[96:111], v[224:227], v[168:171], v[96:111]
	ds_read_b128 v[224:227], v245 offset:160
	s_waitcnt lgkmcnt(3)
	v_mfma_f32_32x32x16_bf16 v[96:111], v[2:5], v[164:167], v[96:111]
	ds_read_b128 v[2:5], v245 offset:192
	s_waitcnt lgkmcnt(3)
	v_mfma_f32_32x32x16_bf16 v[96:111], v[6:9], v[160:163], v[96:111]
	ds_read_b128 v[6:9], v245 offset:224
	s_waitcnt lgkmcnt(3)
	v_mfma_f32_32x32x16_bf16 v[96:111], v[220:223], v[156:159], v[96:111]
	ds_read_b128 v[220:223], v245 offset:256
	s_waitcnt lgkmcnt(3)
	v_mfma_f32_32x32x16_bf16 v[96:111], v[224:227], v[152:155], v[96:111]
	ds_read_b128 v[224:227], v245 offset:288
	s_waitcnt lgkmcnt(3)
	v_mfma_f32_32x32x16_bf16 v[96:111], v[2:5], v[148:151], v[96:111]
	ds_read_b128 v[2:5], v245 offset:320
	s_waitcnt lgkmcnt(3)
	v_mfma_f32_32x32x16_bf16 v[96:111], v[6:9], v[144:147], v[96:111]
	ds_read_b128 v[6:9], v245 offset:352
	s_waitcnt lgkmcnt(3)
	v_mfma_f32_32x32x16_bf16 v[96:111], v[220:223], v[140:143], v[96:111]
	ds_read_b128 v[220:223], v245 offset:384
	s_waitcnt lgkmcnt(3)
	v_mfma_f32_32x32x16_bf16 v[96:111], v[224:227], v[136:139], v[96:111]
	ds_read_b128 v[224:227], v245 offset:416
	s_waitcnt lgkmcnt(3)
	v_mfma_f32_32x32x16_bf16 v[96:111], v[2:5], v[132:135], v[96:111]
	ds_read_b128 v[2:5], v245 offset:448
	s_waitcnt lgkmcnt(3)
	v_mfma_f32_32x32x16_bf16 v[96:111], v[6:9], v[128:131], v[96:111]
	ds_read_b128 v[6:9], v245 offset:480
	s_waitcnt lgkmcnt(3)
	v_mfma_f32_32x32x16_bf16 v[96:111], v[220:223], v[124:127], v[96:111]
	ds_read_b128 v[220:223], v245 offset:16896
	s_waitcnt lgkmcnt(3)
	v_mfma_f32_32x32x16_bf16 v[96:111], v[224:227], v[120:123], v[96:111]
	ds_read_b128 v[224:227], v245 offset:16928
	s_waitcnt lgkmcnt(3)
	v_mfma_f32_32x32x16_bf16 v[96:111], v[2:5], v[116:119], v[96:111]
	ds_read_b128 v[2:5], v245 offset:16960
	s_waitcnt lgkmcnt(3)
	v_mfma_f32_32x32x16_bf16 v[96:111], v[6:9], v[112:115], v[96:111]
	ds_read_b128 v[6:9], v245 offset:16992
	s_waitcnt lgkmcnt(3)
	v_mfma_f32_32x32x16_bf16 v[80:95], v[220:223], v[172:175], 0
	ds_read_b128 v[220:223], v245 offset:17024
	s_waitcnt lgkmcnt(3)
	v_mfma_f32_32x32x16_bf16 v[80:95], v[224:227], v[168:171], v[80:95]
	ds_read_b128 v[224:227], v245 offset:17056
	s_waitcnt lgkmcnt(3)
	v_mfma_f32_32x32x16_bf16 v[80:95], v[2:5], v[164:167], v[80:95]
	ds_read_b128 v[2:5], v245 offset:17088
	s_waitcnt lgkmcnt(3)
	v_mfma_f32_32x32x16_bf16 v[80:95], v[6:9], v[160:163], v[80:95]
	ds_read_b128 v[6:9], v245 offset:17120
	s_waitcnt lgkmcnt(3)
	v_mfma_f32_32x32x16_bf16 v[80:95], v[220:223], v[156:159], v[80:95]
	ds_read_b128 v[220:223], v245 offset:17152
	s_waitcnt lgkmcnt(3)
	v_mfma_f32_32x32x16_bf16 v[80:95], v[224:227], v[152:155], v[80:95]
	ds_read_b128 v[224:227], v245 offset:17184
	s_waitcnt lgkmcnt(3)
	v_mfma_f32_32x32x16_bf16 v[80:95], v[2:5], v[148:151], v[80:95]
	ds_read_b128 v[2:5], v245 offset:17216
	s_waitcnt lgkmcnt(3)
	v_mfma_f32_32x32x16_bf16 v[80:95], v[6:9], v[144:147], v[80:95]
	ds_read_b128 v[6:9], v245 offset:17248
	s_waitcnt lgkmcnt(3)
	v_mfma_f32_32x32x16_bf16 v[80:95], v[220:223], v[140:143], v[80:95]
	ds_read_b128 v[220:223], v245 offset:17280
	s_waitcnt lgkmcnt(3)
	v_mfma_f32_32x32x16_bf16 v[80:95], v[224:227], v[136:139], v[80:95]
	ds_read_b128 v[224:227], v245 offset:17312
	s_waitcnt lgkmcnt(3)
	v_mfma_f32_32x32x16_bf16 v[80:95], v[2:5], v[132:135], v[80:95]
	ds_read_b128 v[2:5], v245 offset:17344
	s_waitcnt lgkmcnt(3)
	v_mfma_f32_32x32x16_bf16 v[80:95], v[6:9], v[128:131], v[80:95]
	ds_read_b128 v[6:9], v245 offset:17376
	s_waitcnt lgkmcnt(3)
	v_mfma_f32_32x32x16_bf16 v[80:95], v[220:223], v[124:127], v[80:95]
	s_waitcnt lgkmcnt(2)
	v_mfma_f32_32x32x16_bf16 v[80:95], v[224:227], v[120:123], v[80:95]
	s_waitcnt lgkmcnt(1)
	v_mfma_f32_32x32x16_bf16 v[80:95], v[2:5], v[116:119], v[80:95]
	s_waitcnt lgkmcnt(0)
	v_mfma_f32_32x32x16_bf16 v[80:95], v[6:9], v[112:115], v[80:95]
	v_max_f32_e32 v0, v97, v97
	v_max_f32_e32 v10, v96, v96
	v_max_f32_e32 v0, v10, v0
	v_max3_f32 v0, v0, v98, v99
	v_max3_f32 v0, v0, v100, v101
	v_max3_f32 v0, v0, v102, v103
	v_max3_f32 v0, v0, v104, v105
	v_max3_f32 v0, v0, v106, v107
	v_max3_f32 v0, v0, v108, v109
	v_max3_f32 v0, v0, v110, v111
	v_and_b32_e32 v3, 64, v218
	v_xor_b32_e32 v2, 32, v218
	v_add_u32_e32 v3, 64, v3
	v_cmp_lt_i32_e32 vcc, v2, v3
	s_nop 1
	v_cndmask_b32_e32 v2, v218, v2, vcc
	v_lshlrev_b32_e32 v2, 2, v2
	s_nop 10
	v_max3_f32 v0, v0, v80, v81
	v_max3_f32 v0, v0, v82, v83
	v_max3_f32 v0, v0, v84, v85
	v_max3_f32 v0, v0, v86, v87
	v_max3_f32 v0, v0, v88, v89
	v_max3_f32 v0, v0, v90, v91
	v_max3_f32 v0, v0, v92, v93
	v_max3_f32 v0, v0, v94, v95
	ds_bpermute_b32 v2, v2, v0
	s_waitcnt lgkmcnt(0)
	v_max3_f32 v0, v236, v0, v2
	v_sub_f32 v4, v97, v0
	v_sub_f32 v3, v96, v0
	v_sub_f32 v5, v100, v0
	v_sub_f32_e32 v2, v236, v0
	v_exp_f32_e32 v8, v4
	v_sub_f32 v4, v98, v0
	v_exp_f32_e32 v3, v3
	v_exp_f32_e32 v9, v4
	v_sub_f32 v4, v99, v0
	v_exp_f32_e32 v11, v5
	v_exp_f32_e32 v10, v4
	v_add_f32 v4, v1, v3
	v_sub_f32 v5, v101, v0
	v_exp_f32_e32 v2, v2
	v_add_f32 v4, v4, v8
	v_exp_f32_e32 v12, v5
	v_add_f32 v4, v4, v9
	v_sub_f32 v5, v102, v0
	v_cvt_pk_bf16_f32 v8, v3, v8
	v_add_f32 v4, v4, v10
	v_exp_f32_e32 v13, v5
	v_add_f32 v4, v4, v11
	v_sub_f32 v5, v103, v0
	v_add_u32_e32 v3, 0x9000, v219
	v_add_f32 v4, v4, v12
	v_exp_f32_e32 v14, v5
	v_add_f32 v4, v4, v13
	v_cvt_pk_bf16_f32 v9, v9, v10
	v_add_f32 v96, v4, v14
	v_sub_f32 v4, v104, v0
	v_add_u32_e32 v104, 0x8000, v219
	v_exp_f32_e32 v97, v4
	v_sub_f32 v4, v105, v0
	v_cvt_pk_bf16_f32 v10, v11, v12
	v_exp_f32_e32 v98, v4
	v_sub_f32 v4, v106, v0
	v_cvt_pk_bf16_f32 v11, v13, v14
	v_exp_f32_e32 v99, v4
	v_sub_f32 v4, v107, v0
	ds_read2_b64 v[12:15], v3 offset0:160 offset1:162
	v_exp_f32_e32 v100, v4
	v_sub_f32 v4, v108, v0
	v_pk_mul_f32 v[64:65], v[64:65], v[2:3] op_sel_hi:[1,0]
	v_pk_mul_f32 v[66:67], v[66:67], v[2:3] op_sel_hi:[1,0]
	v_pk_mul_f32 v[68:69], v[68:69], v[2:3] op_sel_hi:[1,0]
	s_nop 0
	v_exp_f32_e32 v101, v4
	v_sub_f32 v4, v109, v0
	v_pk_mul_f32 v[70:71], v[70:71], v[2:3] op_sel_hi:[1,0]
	v_pk_mul_f32 v[72:73], v[72:73], v[2:3] op_sel_hi:[1,0]
	s_nop 0
	v_exp_f32_e32 v102, v4
	v_sub_f32 v4, v110, v0
	v_pk_mul_f32 v[74:75], v[74:75], v[2:3] op_sel_hi:[1,0]
	v_pk_mul_f32 v[76:77], v[76:77], v[2:3] op_sel_hi:[1,0]
	v_pk_mul_f32 v[78:79], v[78:79], v[2:3] op_sel_hi:[1,0]
	s_nop 0
	v_exp_f32_e32 v103, v4
	ds_read2_b64 v[4:7], v104 offset0:128 offset1:130
	v_add_u32_e32 v105, 0xa000, v219
	s_waitcnt lgkmcnt(0)
	v_mfma_f32_32x32x16_bf16 v[64:79], v[4:7], v[8:11], v[64:79]
	ds_read2_b64 v[4:7], v105 offset0:192 offset1:194
	v_pk_mul_f32 v[48:49], v[48:49], v[2:3] op_sel_hi:[1,0]
	v_pk_mul_f32 v[50:51], v[50:51], v[2:3] op_sel_hi:[1,0]
	v_pk_mul_f32 v[52:53], v[52:53], v[2:3] op_sel_hi:[1,0]
	v_pk_mul_f32 v[54:55], v[54:55], v[2:3] op_sel_hi:[1,0]
	v_pk_mul_f32 v[56:57], v[56:57], v[2:3] op_sel_hi:[1,0]
	v_pk_mul_f32 v[58:59], v[58:59], v[2:3] op_sel_hi:[1,0]
	v_pk_mul_f32 v[60:61], v[60:61], v[2:3] op_sel_hi:[1,0]
	v_pk_mul_f32 v[62:63], v[62:63], v[2:3] op_sel_hi:[1,0]
	v_add_u32_e32 v106, 0xb000, v219
	v_mfma_f32_32x32x16_bf16 v[48:63], v[12:15], v[8:11], v[48:63]
	ds_read2_b64 v[12:15], v106 offset0:224 offset1:226
	v_pk_mul_f32 v[32:33], v[32:33], v[2:3] op_sel_hi:[1,0]
	v_pk_mul_f32 v[34:35], v[34:35], v[2:3] op_sel_hi:[1,0]
	v_pk_mul_f32 v[36:37], v[36:37], v[2:3] op_sel_hi:[1,0]
	v_pk_mul_f32 v[38:39], v[38:39], v[2:3] op_sel_hi:[1,0]
	v_pk_mul_f32 v[40:41], v[40:41], v[2:3] op_sel_hi:[1,0]
	v_pk_mul_f32 v[42:43], v[42:43], v[2:3] op_sel_hi:[1,0]
	v_pk_mul_f32 v[44:45], v[44:45], v[2:3] op_sel_hi:[1,0]
	v_pk_mul_f32 v[46:47], v[46:47], v[2:3] op_sel_hi:[1,0]
	v_pk_mul_f32 v[16:17], v[16:17], v[2:3] op_sel_hi:[1,0]
	v_pk_mul_f32 v[18:19], v[18:19], v[2:3] op_sel_hi:[1,0]
	v_pk_mul_f32 v[20:21], v[20:21], v[2:3] op_sel_hi:[1,0]
	s_waitcnt lgkmcnt(1)
	v_mfma_f32_32x32x16_bf16 v[32:47], v[4:7], v[8:11], v[32:47]
	ds_read2_b64 v[4:7], v104 offset0:132 offset1:134
	v_pk_mul_f32 v[22:23], v[22:23], v[2:3] op_sel_hi:[1,0]
	v_pk_mul_f32 v[24:25], v[24:25], v[2:3] op_sel_hi:[1,0]
	v_pk_mul_f32 v[26:27], v[26:27], v[2:3] op_sel_hi:[1,0]
	v_pk_mul_f32 v[28:29], v[28:29], v[2:3] op_sel_hi:[1,0]
	v_pk_mul_f32 v[30:31], v[30:31], v[2:3] op_sel_hi:[1,0]
	v_mov_b32_e32 v236, v0
	s_waitcnt lgkmcnt(1)
	v_mfma_f32_32x32x16_bf16 v[16:31], v[12:15], v[8:11], v[16:31]
	v_sub_f32 v8, v111, v0
	v_cvt_pk_bf16_f32 v9, v99, v100
	v_exp_f32_e32 v107, v8
	v_cvt_pk_bf16_f32 v8, v97, v98
	v_cvt_pk_bf16_f32 v10, v101, v102
	ds_read2_b64 v[12:15], v3 offset0:164 offset1:166
	v_cvt_pk_bf16_f32 v11, v103, v107
	s_waitcnt lgkmcnt(1)
	s_nop 0
	v_mfma_f32_32x32x16_bf16 v[64:79], v[4:7], v[8:11], v[64:79]
	v_add_f32 v4, v96, v97
	s_nop 0
	v_add_f32 v4, v4, v98
	s_nop 0
	v_add_f32 v4, v4, v99
	s_nop 0
	v_add_f32 v96, v4, v100
	v_sub_f32 v4, v80, v0
	s_waitcnt lgkmcnt(0)
	v_mfma_f32_32x32x16_bf16 v[48:63], v[12:15], v[8:11], v[48:63]
	v_exp_f32_e32 v80, v4
	ds_read2_b64 v[4:7], v105 offset0:196 offset1:198
	v_sub_f32 v12, v81, v0
	s_nop 0
	v_exp_f32_e32 v81, v12
	v_sub_f32 v12, v82, v0
	s_nop 0
	v_exp_f32_e32 v82, v12
	v_sub_f32 v12, v83, v0
	s_waitcnt lgkmcnt(0)
	v_mfma_f32_32x32x16_bf16 v[32:47], v[4:7], v[8:11], v[32:47]
	v_exp_f32_e32 v83, v12
	ds_read2_b64 v[12:15], v106 offset0:228 offset1:230
	v_sub_f32 v4, v84, v0
	s_nop 0
	v_exp_f32_e32 v84, v4
	v_sub_f32 v4, v85, v0
	s_nop 0
	v_exp_f32_e32 v85, v4
	v_sub_f32 v4, v86, v0
	s_waitcnt lgkmcnt(0)
	v_mfma_f32_32x32x16_bf16 v[16:31], v[12:15], v[8:11], v[16:31]
	v_exp_f32_e32 v86, v4
	ds_read2_b64 v[4:7], v104 offset0:136 offset1:138
	v_sub_f32 v8, v87, v0
	ds_read2_b64 v[12:15], v3 offset0:168 offset1:170
	v_exp_f32_e32 v87, v8
	v_cvt_pk_bf16_f32 v8, v80, v81
	v_cvt_pk_bf16_f32 v9, v82, v83
	v_cvt_pk_bf16_f32 v10, v84, v85
	v_cvt_pk_bf16_f32 v11, v86, v87
	s_waitcnt lgkmcnt(1)
	s_nop 0
	v_mfma_f32_32x32x16_bf16 v[64:79], v[4:7], v[8:11], v[64:79]
	v_add_f32 v4, v96, v101
	s_nop 0
	v_add_f32 v4, v4, v102
	s_nop 0
	v_add_f32 v4, v4, v103
	s_nop 0
	v_add_f32 v96, v4, v107
	v_sub_f32 v4, v88, v0
	s_waitcnt lgkmcnt(0)
	v_mfma_f32_32x32x16_bf16 v[48:63], v[12:15], v[8:11], v[48:63]
	v_exp_f32_e32 v88, v4
	ds_read2_b64 v[4:7], v105 offset0:200 offset1:202
	v_sub_f32 v12, v89, v0
	s_nop 0
	v_exp_f32_e32 v89, v12
	v_sub_f32 v12, v90, v0
	s_nop 0
	v_exp_f32_e32 v90, v12
	v_sub_f32 v12, v91, v0
	s_waitcnt lgkmcnt(0)
	v_mfma_f32_32x32x16_bf16 v[32:47], v[4:7], v[8:11], v[32:47]
	v_exp_f32_e32 v91, v12
	ds_read2_b64 v[12:15], v106 offset0:232 offset1:234
	v_sub_f32 v4, v92, v0
	s_nop 0
	v_exp_f32_e32 v92, v4
	v_sub_f32 v4, v93, v0
	s_nop 0
	v_exp_f32_e32 v93, v4
	v_sub_f32 v4, v94, v0
	s_waitcnt lgkmcnt(0)
	v_mfma_f32_32x32x16_bf16 v[16:31], v[12:15], v[8:11], v[16:31]
	v_exp_f32_e32 v94, v4
	ds_read2_b64 v[4:7], v104 offset0:140 offset1:142
	ds_read2_b64 v[12:15], v3 offset0:172 offset1:174
	v_sub_f32 v8, v95, v0
	v_cvt_pk_bf16_f32 v9, v90, v91
	v_exp_f32_e32 v95, v8
	v_cvt_pk_bf16_f32 v8, v88, v89
	v_cvt_pk_bf16_f32 v10, v92, v93
	v_add_f32 v3, v96, v80
	v_cvt_pk_bf16_f32 v11, v94, v95
	v_add_f32 v3, v3, v81
	s_nop 0
	v_add_f32 v3, v3, v82
	s_waitcnt lgkmcnt(1)
	v_mfma_f32_32x32x16_bf16 v[64:79], v[4:7], v[8:11], v[64:79]
	ds_read2_b64 v[4:7], v105 offset0:204 offset1:206
	v_add_f32 v3, v3, v83
	s_nop 0
	v_add_f32 v3, v3, v84
	s_nop 0
	v_add_f32 v3, v3, v85
	s_waitcnt lgkmcnt(1)
	v_mfma_f32_32x32x16_bf16 v[48:63], v[12:15], v[8:11], v[48:63]
	ds_read2_b64 v[12:15], v106 offset0:236 offset1:238
	v_add_f32 v3, v3, v86
	s_nop 0
	v_add_f32 v3, v3, v87
	s_nop 0
	v_add_f32 v3, v3, v88
	s_nop 0
	v_add_f32 v3, v3, v89
	s_waitcnt lgkmcnt(1)
	v_mfma_f32_32x32x16_bf16 v[32:47], v[4:7], v[8:11], v[32:47]
	v_add_f32 v3, v3, v90
	s_nop 0
	v_add_f32 v3, v3, v91
	s_nop 0
	v_add_f32 v3, v3, v92
	s_nop 0
	v_add_f32 v3, v3, v93
	s_waitcnt lgkmcnt(0)
	v_mfma_f32_32x32x16_bf16 v[16:31], v[12:15], v[8:11], v[16:31]
	v_add_f32 v3, v3, v94
	s_nop 0
	v_add_f32 v3, v3, v95
	s_nop 0
	v_fmac_f32_e32 v3, v246, v2
	v_mov_b32_e32 v246, v3
	s_branch .LBB0_310

.LBB0_566:
	s_and_saveexec_b64 s[22:23], vcc
	s_cbranch_execz .LBB0_555
	ds_read_b128 v[196:199], v188
	ds_read_b128 v[202:205], v188 offset:32
	ds_read_b128 v[206:209], v188 offset:64
	ds_read_b128 v[210:213], v188 offset:96
	ds_read_b128 v[220:223], v188 offset:128
	ds_read_b128 v[224:227], v188 offset:160
	ds_read_b128 v[2:5], v188 offset:192
	ds_read_b128 v[6:9], v188 offset:224
	s_waitcnt lgkmcnt(7)
	v_mfma_f32_32x32x16_bf16 v[96:111], v[196:199], v[148:151], 0
	ds_read_b128 v[196:199], v188 offset:256
	s_waitcnt lgkmcnt(7)
	v_mfma_f32_32x32x16_bf16 v[96:111], v[202:205], v[144:147], v[96:111]
	ds_read_b128 v[202:205], v188 offset:288
	s_waitcnt lgkmcnt(7)
	v_mfma_f32_32x32x16_bf16 v[96:111], v[206:209], v[140:143], v[96:111]
	ds_read_b128 v[206:209], v188 offset:10752
	s_waitcnt lgkmcnt(7)
	v_mfma_f32_32x32x16_bf16 v[96:111], v[210:213], v[136:139], v[96:111]
	ds_read_b128 v[210:213], v188 offset:10784
	s_waitcnt lgkmcnt(7)
	v_mfma_f32_32x32x16_bf16 v[96:111], v[220:223], v[132:135], v[96:111]
	ds_read_b128 v[220:223], v188 offset:10816
	s_waitcnt lgkmcnt(7)
	v_mfma_f32_32x32x16_bf16 v[96:111], v[224:227], v[128:131], v[96:111]
	ds_read_b128 v[224:227], v188 offset:10848
	s_waitcnt lgkmcnt(7)
	v_mfma_f32_32x32x16_bf16 v[96:111], v[2:5], v[124:127], v[96:111]
	ds_read_b128 v[2:5], v188 offset:10880
	s_waitcnt lgkmcnt(7)
	v_mfma_f32_32x32x16_bf16 v[96:111], v[6:9], v[120:123], v[96:111]
	ds_read_b128 v[6:9], v188 offset:10912
	s_waitcnt lgkmcnt(7)
	v_mfma_f32_32x32x16_bf16 v[96:111], v[196:199], v[116:119], v[96:111]
	ds_read_b128 v[196:199], v188 offset:10944
	s_waitcnt lgkmcnt(7)
	v_mfma_f32_32x32x16_bf16 v[96:111], v[202:205], v[112:115], v[96:111]
	ds_read_b128 v[202:205], v188 offset:10976
	s_waitcnt lgkmcnt(7)
	v_mfma_f32_32x32x16_bf16 v[80:95], v[206:209], v[148:151], 0
	ds_read_b128 v[206:209], v188 offset:11008
	s_waitcnt lgkmcnt(7)
	v_mfma_f32_32x32x16_bf16 v[80:95], v[210:213], v[144:147], v[80:95]
	ds_read_b128 v[210:213], v188 offset:11040
	s_waitcnt lgkmcnt(7)
	v_mfma_f32_32x32x16_bf16 v[80:95], v[220:223], v[140:143], v[80:95]
	s_waitcnt lgkmcnt(6)
	v_mfma_f32_32x32x16_bf16 v[80:95], v[224:227], v[136:139], v[80:95]
	s_waitcnt lgkmcnt(5)
	v_mfma_f32_32x32x16_bf16 v[80:95], v[2:5], v[132:135], v[80:95]
	s_waitcnt lgkmcnt(4)
	v_mfma_f32_32x32x16_bf16 v[80:95], v[6:9], v[128:131], v[80:95]
	s_waitcnt lgkmcnt(3)
	v_mfma_f32_32x32x16_bf16 v[80:95], v[196:199], v[124:127], v[80:95]
	v_max_f32_e32 v0, v97, v97
	v_max_f32_e32 v10, v96, v96
	v_max_f32_e32 v0, v10, v0
	v_max3_f32 v0, v0, v98, v99
	v_max3_f32 v0, v0, v100, v101
	v_max3_f32 v0, v0, v102, v103
	v_max3_f32 v0, v0, v104, v105
	v_max3_f32 v0, v0, v106, v107
	v_max3_f32 v0, v0, v108, v109
	v_max3_f32 v0, v0, v110, v111
	v_and_b32_e32 v3, 64, v218
	v_xor_b32_e32 v2, 32, v218
	v_add_u32_e32 v3, 64, v3
	v_cmp_lt_i32_e64 s[12:13], v2, v3
	s_nop 1
	v_cndmask_b32_e64 v2, v218, v2, s[12:13]
	s_waitcnt lgkmcnt(2)
	v_mfma_f32_32x32x16_bf16 v[80:95], v[202:205], v[120:123], v[80:95]
	s_waitcnt lgkmcnt(1)
	v_mfma_f32_32x32x16_bf16 v[80:95], v[206:209], v[116:119], v[80:95]
	s_waitcnt lgkmcnt(0)
	v_mfma_f32_32x32x16_bf16 v[80:95], v[210:213], v[112:115], v[80:95]
	v_lshlrev_b32_e32 v2, 2, v2
	s_nop 10
	v_max3_f32 v0, v0, v80, v81
	v_max3_f32 v0, v0, v82, v83
	v_max3_f32 v0, v0, v84, v85
	v_max3_f32 v0, v0, v86, v87
	v_max3_f32 v0, v0, v88, v89
	v_max3_f32 v0, v0, v90, v91
	v_max3_f32 v0, v0, v92, v93
	v_max3_f32 v0, v0, v94, v95
	ds_bpermute_b32 v2, v2, v0
	s_waitcnt lgkmcnt(0)
	v_max3_f32 v0, v195, v0, v2
	v_sub_f32 v4, v97, v0
	v_sub_f32 v3, v96, v0
	v_sub_f32 v5, v100, v0
	v_sub_f32_e32 v2, v195, v0
	v_exp_f32_e32 v8, v4
	v_sub_f32 v4, v98, v0
	v_exp_f32_e32 v3, v3
	v_exp_f32_e32 v9, v4
	v_sub_f32 v4, v99, v0
	v_exp_f32_e32 v11, v5
	v_exp_f32_e32 v10, v4
	v_add_f32 v4, v1, v3
	v_sub_f32 v5, v101, v0
	v_exp_f32_e32 v2, v2
	v_add_f32 v4, v4, v8
	v_exp_f32_e32 v12, v5
	v_add_f32 v4, v4, v9
	v_sub_f32 v5, v102, v0
	v_cvt_pk_bf16_f32 v8, v3, v8
	v_add_f32 v4, v4, v10
	v_exp_f32_e32 v13, v5
	v_add_f32 v4, v4, v11
	v_sub_f32 v5, v103, v0
	v_add_u32_e32 v3, 0x6000, v194
	v_add_f32 v4, v4, v12
	v_exp_f32_e32 v14, v5
	v_add_f32 v4, v4, v13
	v_cvt_pk_bf16_f32 v9, v9, v10
	v_add_f32 v96, v4, v14
	v_sub_f32 v4, v104, v0
	v_add_u32_e32 v104, 0x5000, v194
	v_exp_f32_e32 v97, v4
	v_sub_f32 v4, v105, v0
	v_cvt_pk_bf16_f32 v10, v11, v12
	v_exp_f32_e32 v98, v4
	v_sub_f32 v4, v106, v0
	v_cvt_pk_bf16_f32 v11, v13, v14
	v_exp_f32_e32 v99, v4
	v_sub_f32 v4, v107, v0
	ds_read2_b64 v[12:15], v3 offset0:160 offset1:162
	v_exp_f32_e32 v100, v4
	v_sub_f32 v4, v108, v0
	v_pk_mul_f32 v[64:65], v[64:65], v[2:3] op_sel_hi:[1,0]
	v_pk_mul_f32 v[66:67], v[66:67], v[2:3] op_sel_hi:[1,0]
	v_pk_mul_f32 v[68:69], v[68:69], v[2:3] op_sel_hi:[1,0]
	s_nop 0
	v_exp_f32_e32 v101, v4
	v_sub_f32 v4, v109, v0
	v_pk_mul_f32 v[70:71], v[70:71], v[2:3] op_sel_hi:[1,0]
	v_pk_mul_f32 v[72:73], v[72:73], v[2:3] op_sel_hi:[1,0]
	s_nop 0
	v_exp_f32_e32 v102, v4
	v_sub_f32 v4, v110, v0
	v_pk_mul_f32 v[74:75], v[74:75], v[2:3] op_sel_hi:[1,0]
	v_pk_mul_f32 v[76:77], v[76:77], v[2:3] op_sel_hi:[1,0]
	v_pk_mul_f32 v[78:79], v[78:79], v[2:3] op_sel_hi:[1,0]
	s_nop 0
	v_exp_f32_e32 v103, v4
	ds_read2_b64 v[4:7], v104 offset0:128 offset1:130
	v_add_u32_e32 v105, 0x7000, v194
	s_waitcnt lgkmcnt(0)
	v_mfma_f32_32x32x16_bf16 v[64:79], v[4:7], v[8:11], v[64:79]
	ds_read2_b64 v[4:7], v105 offset0:192 offset1:194
	v_pk_mul_f32 v[48:49], v[48:49], v[2:3] op_sel_hi:[1,0]
	v_pk_mul_f32 v[50:51], v[50:51], v[2:3] op_sel_hi:[1,0]
	v_pk_mul_f32 v[52:53], v[52:53], v[2:3] op_sel_hi:[1,0]
	v_pk_mul_f32 v[54:55], v[54:55], v[2:3] op_sel_hi:[1,0]
	v_pk_mul_f32 v[56:57], v[56:57], v[2:3] op_sel_hi:[1,0]
	v_pk_mul_f32 v[58:59], v[58:59], v[2:3] op_sel_hi:[1,0]
	v_pk_mul_f32 v[60:61], v[60:61], v[2:3] op_sel_hi:[1,0]
	v_pk_mul_f32 v[62:63], v[62:63], v[2:3] op_sel_hi:[1,0]
	v_add_u32_e32 v106, 0x8000, v194
	v_mfma_f32_32x32x16_bf16 v[48:63], v[12:15], v[8:11], v[48:63]
	ds_read2_b64 v[12:15], v106 offset0:224 offset1:226
	v_pk_mul_f32 v[32:33], v[32:33], v[2:3] op_sel_hi:[1,0]
	v_pk_mul_f32 v[34:35], v[34:35], v[2:3] op_sel_hi:[1,0]
	v_pk_mul_f32 v[36:37], v[36:37], v[2:3] op_sel_hi:[1,0]
	v_pk_mul_f32 v[38:39], v[38:39], v[2:3] op_sel_hi:[1,0]
	v_pk_mul_f32 v[40:41], v[40:41], v[2:3] op_sel_hi:[1,0]
	v_pk_mul_f32 v[42:43], v[42:43], v[2:3] op_sel_hi:[1,0]
	v_pk_mul_f32 v[44:45], v[44:45], v[2:3] op_sel_hi:[1,0]
	v_pk_mul_f32 v[46:47], v[46:47], v[2:3] op_sel_hi:[1,0]
	v_pk_mul_f32 v[16:17], v[16:17], v[2:3] op_sel_hi:[1,0]
	v_pk_mul_f32 v[18:19], v[18:19], v[2:3] op_sel_hi:[1,0]
	v_pk_mul_f32 v[20:21], v[20:21], v[2:3] op_sel_hi:[1,0]
	s_waitcnt lgkmcnt(1)
	v_mfma_f32_32x32x16_bf16 v[32:47], v[4:7], v[8:11], v[32:47]
	ds_read2_b64 v[4:7], v104 offset0:132 offset1:134
	v_pk_mul_f32 v[22:23], v[22:23], v[2:3] op_sel_hi:[1,0]
	v_pk_mul_f32 v[24:25], v[24:25], v[2:3] op_sel_hi:[1,0]
	v_pk_mul_f32 v[26:27], v[26:27], v[2:3] op_sel_hi:[1,0]
	v_pk_mul_f32 v[28:29], v[28:29], v[2:3] op_sel_hi:[1,0]
	v_pk_mul_f32 v[30:31], v[30:31], v[2:3] op_sel_hi:[1,0]
	v_mov_b32_e32 v195, v0
	s_waitcnt lgkmcnt(1)
	v_mfma_f32_32x32x16_bf16 v[16:31], v[12:15], v[8:11], v[16:31]
	v_sub_f32 v8, v111, v0
	v_cvt_pk_bf16_f32 v9, v99, v100
	v_exp_f32_e32 v107, v8
	v_cvt_pk_bf16_f32 v8, v97, v98
	v_cvt_pk_bf16_f32 v10, v101, v102
	ds_read2_b64 v[12:15], v3 offset0:164 offset1:166
	v_cvt_pk_bf16_f32 v11, v103, v107
	s_waitcnt lgkmcnt(1)
	s_nop 0
	v_mfma_f32_32x32x16_bf16 v[64:79], v[4:7], v[8:11], v[64:79]
	v_add_f32 v4, v96, v97
	s_nop 0
	v_add_f32 v4, v4, v98
	s_nop 0
	v_add_f32 v4, v4, v99
	s_nop 0
	v_add_f32 v96, v4, v100
	v_sub_f32 v4, v80, v0
	s_waitcnt lgkmcnt(0)
	v_mfma_f32_32x32x16_bf16 v[48:63], v[12:15], v[8:11], v[48:63]
	v_exp_f32_e32 v80, v4
	ds_read2_b64 v[4:7], v105 offset0:196 offset1:198
	v_sub_f32 v12, v81, v0
	s_nop 0
	v_exp_f32_e32 v81, v12
	v_sub_f32 v12, v82, v0
	s_nop 0
	v_exp_f32_e32 v82, v12
	v_sub_f32 v12, v83, v0
	s_waitcnt lgkmcnt(0)
	v_mfma_f32_32x32x16_bf16 v[32:47], v[4:7], v[8:11], v[32:47]
	v_exp_f32_e32 v83, v12
	ds_read2_b64 v[12:15], v106 offset0:228 offset1:230
	v_sub_f32 v4, v84, v0
	s_nop 0
	v_exp_f32_e32 v84, v4
	v_sub_f32 v4, v85, v0
	s_nop 0
	v_exp_f32_e32 v85, v4
	v_sub_f32 v4, v86, v0
	s_waitcnt lgkmcnt(0)
	v_mfma_f32_32x32x16_bf16 v[16:31], v[12:15], v[8:11], v[16:31]
	v_exp_f32_e32 v86, v4
	ds_read2_b64 v[4:7], v104 offset0:136 offset1:138
	v_sub_f32 v8, v87, v0
	ds_read2_b64 v[12:15], v3 offset0:168 offset1:170
	v_exp_f32_e32 v87, v8
	v_cvt_pk_bf16_f32 v8, v80, v81
	v_cvt_pk_bf16_f32 v9, v82, v83
	v_cvt_pk_bf16_f32 v10, v84, v85
	v_cvt_pk_bf16_f32 v11, v86, v87
	s_waitcnt lgkmcnt(1)
	s_nop 0
	v_mfma_f32_32x32x16_bf16 v[64:79], v[4:7], v[8:11], v[64:79]
	v_add_f32 v4, v96, v101
	s_nop 0
	v_add_f32 v4, v4, v102
	s_nop 0
	v_add_f32 v4, v4, v103
	s_nop 0
	v_add_f32 v96, v4, v107
	v_sub_f32 v4, v88, v0
	s_waitcnt lgkmcnt(0)
	v_mfma_f32_32x32x16_bf16 v[48:63], v[12:15], v[8:11], v[48:63]
	v_exp_f32_e32 v88, v4
	ds_read2_b64 v[4:7], v105 offset0:200 offset1:202
	v_sub_f32 v12, v89, v0
	s_nop 0
	v_exp_f32_e32 v89, v12
	v_sub_f32 v12, v90, v0
	s_nop 0
	v_exp_f32_e32 v90, v12
	v_sub_f32 v12, v91, v0
	s_waitcnt lgkmcnt(0)
	v_mfma_f32_32x32x16_bf16 v[32:47], v[4:7], v[8:11], v[32:47]
	v_exp_f32_e32 v91, v12
	ds_read2_b64 v[12:15], v106 offset0:232 offset1:234
	v_sub_f32 v4, v92, v0
	s_nop 0
	v_exp_f32_e32 v92, v4
	v_sub_f32 v4, v93, v0
	s_nop 0
	v_exp_f32_e32 v93, v4
	v_sub_f32 v4, v94, v0
	s_waitcnt lgkmcnt(0)
	v_mfma_f32_32x32x16_bf16 v[16:31], v[12:15], v[8:11], v[16:31]
	v_exp_f32_e32 v94, v4
	ds_read2_b64 v[4:7], v104 offset0:140 offset1:142
	ds_read2_b64 v[12:15], v3 offset0:172 offset1:174
	v_sub_f32 v8, v95, v0
	v_cvt_pk_bf16_f32 v9, v90, v91
	v_exp_f32_e32 v95, v8
	v_cvt_pk_bf16_f32 v8, v88, v89
	v_cvt_pk_bf16_f32 v10, v92, v93
	v_add_f32 v3, v96, v80
	v_cvt_pk_bf16_f32 v11, v94, v95
	v_add_f32 v3, v3, v81
	s_nop 0
	v_add_f32 v3, v3, v82
	s_waitcnt lgkmcnt(1)
	v_mfma_f32_32x32x16_bf16 v[64:79], v[4:7], v[8:11], v[64:79]
	ds_read2_b64 v[4:7], v105 offset0:204 offset1:206
	v_add_f32 v3, v3, v83
	s_nop 0
	v_add_f32 v3, v3, v84
	s_nop 0
	v_add_f32 v3, v3, v85
	s_waitcnt lgkmcnt(1)
	v_mfma_f32_32x32x16_bf16 v[48:63], v[12:15], v[8:11], v[48:63]
	ds_read2_b64 v[12:15], v106 offset0:236 offset1:238
	v_add_f32 v3, v3, v86
	s_nop 0
	v_add_f32 v3, v3, v87
	s_nop 0
	v_add_f32 v3, v3, v88
	s_nop 0
	v_add_f32 v3, v3, v89
	s_waitcnt lgkmcnt(1)
	v_mfma_f32_32x32x16_bf16 v[32:47], v[4:7], v[8:11], v[32:47]
	v_add_f32 v3, v3, v90
	s_nop 0
	v_add_f32 v3, v3, v91
	s_nop 0
	v_add_f32 v3, v3, v92
	s_nop 0
	v_add_f32 v3, v3, v93
	s_waitcnt lgkmcnt(0)
	v_mfma_f32_32x32x16_bf16 v[16:31], v[12:15], v[8:11], v[16:31]
	v_add_f32 v3, v3, v94
	s_nop 0
	v_add_f32 v3, v3, v95
	s_nop 0
	v_fmac_f32_e32 v3, v184, v2
	v_mov_b32_e32 v184, v3
	s_branch .LBB0_555

.LBB0_598:
	s_and_saveexec_b64 s[24:25], s[6:7]
	s_cbranch_execz .LBB0_587
	ds_read_b128 v[194:197], v185
	ds_read_b128 v[202:205], v185 offset:32
	ds_read_b128 v[206:209], v185 offset:64
	ds_read_b128 v[210:213], v185 offset:96
	ds_read_b128 v[220:223], v185 offset:128
	ds_read_b128 v[224:227], v185 offset:160
	ds_read_b128 v[2:5], v185 offset:192
	ds_read_b128 v[6:9], v185 offset:224
	s_waitcnt lgkmcnt(7)
	v_mfma_f32_32x32x16_bf16 v[96:111], v[194:197], v[148:151], 0
	ds_read_b128 v[194:197], v185 offset:256
	s_waitcnt lgkmcnt(7)
	v_mfma_f32_32x32x16_bf16 v[96:111], v[202:205], v[144:147], v[96:111]
	ds_read_b128 v[202:205], v185 offset:288
	s_waitcnt lgkmcnt(7)
	v_mfma_f32_32x32x16_bf16 v[96:111], v[206:209], v[140:143], v[96:111]
	ds_read_b128 v[206:209], v185 offset:10752
	s_waitcnt lgkmcnt(7)
	v_mfma_f32_32x32x16_bf16 v[96:111], v[210:213], v[136:139], v[96:111]
	ds_read_b128 v[210:213], v185 offset:10784
	s_waitcnt lgkmcnt(7)
	v_mfma_f32_32x32x16_bf16 v[96:111], v[220:223], v[132:135], v[96:111]
	ds_read_b128 v[220:223], v185 offset:10816
	s_waitcnt lgkmcnt(7)
	v_mfma_f32_32x32x16_bf16 v[96:111], v[224:227], v[128:131], v[96:111]
	ds_read_b128 v[224:227], v185 offset:10848
	s_waitcnt lgkmcnt(7)
	v_mfma_f32_32x32x16_bf16 v[96:111], v[2:5], v[124:127], v[96:111]
	ds_read_b128 v[2:5], v185 offset:10880
	s_waitcnt lgkmcnt(7)
	v_mfma_f32_32x32x16_bf16 v[96:111], v[6:9], v[120:123], v[96:111]
	ds_read_b128 v[6:9], v185 offset:10912
	s_waitcnt lgkmcnt(7)
	v_mfma_f32_32x32x16_bf16 v[96:111], v[194:197], v[116:119], v[96:111]
	ds_read_b128 v[194:197], v185 offset:10944
	s_waitcnt lgkmcnt(7)
	v_mfma_f32_32x32x16_bf16 v[96:111], v[202:205], v[112:115], v[96:111]
	ds_read_b128 v[202:205], v185 offset:10976
	s_waitcnt lgkmcnt(7)
	v_mfma_f32_32x32x16_bf16 v[80:95], v[206:209], v[148:151], 0
	ds_read_b128 v[206:209], v185 offset:11008
	s_waitcnt lgkmcnt(7)
	v_mfma_f32_32x32x16_bf16 v[80:95], v[210:213], v[144:147], v[80:95]
	ds_read_b128 v[210:213], v185 offset:11040
	s_waitcnt lgkmcnt(7)
	v_mfma_f32_32x32x16_bf16 v[80:95], v[220:223], v[140:143], v[80:95]
	s_waitcnt lgkmcnt(6)
	v_mfma_f32_32x32x16_bf16 v[80:95], v[224:227], v[136:139], v[80:95]
	s_waitcnt lgkmcnt(5)
	v_mfma_f32_32x32x16_bf16 v[80:95], v[2:5], v[132:135], v[80:95]
	s_waitcnt lgkmcnt(4)
	v_mfma_f32_32x32x16_bf16 v[80:95], v[6:9], v[128:131], v[80:95]
	s_waitcnt lgkmcnt(3)
	v_mfma_f32_32x32x16_bf16 v[80:95], v[194:197], v[124:127], v[80:95]
	v_max_f32_e32 v0, v97, v97
	v_max_f32_e32 v10, v96, v96
	v_max_f32_e32 v0, v10, v0
	v_max3_f32 v0, v0, v98, v99
	v_max3_f32 v0, v0, v100, v101
	v_max3_f32 v0, v0, v102, v103
	v_max3_f32 v0, v0, v104, v105
	v_max3_f32 v0, v0, v106, v107
	v_max3_f32 v0, v0, v108, v109
	v_max3_f32 v0, v0, v110, v111
	v_and_b32_e32 v3, 64, v218
	v_xor_b32_e32 v2, 32, v218
	v_add_u32_e32 v3, 64, v3
	v_cmp_lt_i32_e32 vcc, v2, v3
	s_nop 1
	v_cndmask_b32_e32 v2, v218, v2, vcc
	s_waitcnt lgkmcnt(2)
	v_mfma_f32_32x32x16_bf16 v[80:95], v[202:205], v[120:123], v[80:95]
	s_waitcnt lgkmcnt(1)
	v_mfma_f32_32x32x16_bf16 v[80:95], v[206:209], v[116:119], v[80:95]
	s_waitcnt lgkmcnt(0)
	v_mfma_f32_32x32x16_bf16 v[80:95], v[210:213], v[112:115], v[80:95]
	v_lshlrev_b32_e32 v2, 2, v2
	s_nop 10
	v_max3_f32 v0, v0, v80, v81
	v_max3_f32 v0, v0, v82, v83
	v_max3_f32 v0, v0, v84, v85
	v_max3_f32 v0, v0, v86, v87
	v_max3_f32 v0, v0, v88, v89
	v_max3_f32 v0, v0, v90, v91
	v_max3_f32 v0, v0, v92, v93
	v_max3_f32 v0, v0, v94, v95
	ds_bpermute_b32 v2, v2, v0
	s_waitcnt lgkmcnt(0)
	v_max3_f32 v0, v192, v0, v2
	v_sub_f32 v4, v97, v0
	v_sub_f32 v3, v96, v0
	v_sub_f32 v5, v100, v0
	v_sub_f32_e32 v2, v192, v0
	v_exp_f32_e32 v8, v4
	v_sub_f32 v4, v98, v0
	v_exp_f32_e32 v3, v3
	v_exp_f32_e32 v9, v4
	v_sub_f32 v4, v99, v0
	v_exp_f32_e32 v11, v5
	v_exp_f32_e32 v10, v4
	v_add_f32 v4, v1, v3
	v_sub_f32 v5, v101, v0
	v_exp_f32_e32 v2, v2
	v_add_f32 v4, v4, v8
	v_exp_f32_e32 v12, v5
	v_add_f32 v4, v4, v9
	v_sub_f32 v5, v102, v0
	v_cvt_pk_bf16_f32 v8, v3, v8
	v_add_f32 v4, v4, v10
	v_exp_f32_e32 v13, v5
	v_add_f32 v4, v4, v11
	v_sub_f32 v5, v103, v0
	v_add_u32_e32 v3, 0x6000, v191
	v_add_f32 v4, v4, v12
	v_exp_f32_e32 v14, v5
	v_add_f32 v4, v4, v13
	v_cvt_pk_bf16_f32 v9, v9, v10
	v_add_f32 v96, v4, v14
	v_sub_f32 v4, v104, v0
	v_add_u32_e32 v104, 0x5000, v191
	v_exp_f32_e32 v97, v4
	v_sub_f32 v4, v105, v0
	v_cvt_pk_bf16_f32 v10, v11, v12
	v_exp_f32_e32 v98, v4
	v_sub_f32 v4, v106, v0
	v_cvt_pk_bf16_f32 v11, v13, v14
	v_exp_f32_e32 v99, v4
	v_sub_f32 v4, v107, v0
	ds_read2_b64 v[12:15], v3 offset0:160 offset1:162
	v_exp_f32_e32 v100, v4
	v_sub_f32 v4, v108, v0
	v_pk_mul_f32 v[64:65], v[64:65], v[2:3] op_sel_hi:[1,0]
	v_pk_mul_f32 v[66:67], v[66:67], v[2:3] op_sel_hi:[1,0]
	v_pk_mul_f32 v[68:69], v[68:69], v[2:3] op_sel_hi:[1,0]
	s_nop 0
	v_exp_f32_e32 v101, v4
	v_sub_f32 v4, v109, v0
	v_pk_mul_f32 v[70:71], v[70:71], v[2:3] op_sel_hi:[1,0]
	v_pk_mul_f32 v[72:73], v[72:73], v[2:3] op_sel_hi:[1,0]
	s_nop 0
	v_exp_f32_e32 v102, v4
	v_sub_f32 v4, v110, v0
	v_pk_mul_f32 v[74:75], v[74:75], v[2:3] op_sel_hi:[1,0]
	v_pk_mul_f32 v[76:77], v[76:77], v[2:3] op_sel_hi:[1,0]
	v_pk_mul_f32 v[78:79], v[78:79], v[2:3] op_sel_hi:[1,0]
	s_nop 0
	v_exp_f32_e32 v103, v4
	ds_read2_b64 v[4:7], v104 offset0:128 offset1:130
	v_add_u32_e32 v105, 0x7000, v191
	s_waitcnt lgkmcnt(0)
	v_mfma_f32_32x32x16_bf16 v[64:79], v[4:7], v[8:11], v[64:79]
	ds_read2_b64 v[4:7], v105 offset0:192 offset1:194
	v_pk_mul_f32 v[48:49], v[48:49], v[2:3] op_sel_hi:[1,0]
	v_pk_mul_f32 v[50:51], v[50:51], v[2:3] op_sel_hi:[1,0]
	v_pk_mul_f32 v[52:53], v[52:53], v[2:3] op_sel_hi:[1,0]
	v_pk_mul_f32 v[54:55], v[54:55], v[2:3] op_sel_hi:[1,0]
	v_pk_mul_f32 v[56:57], v[56:57], v[2:3] op_sel_hi:[1,0]
	v_pk_mul_f32 v[58:59], v[58:59], v[2:3] op_sel_hi:[1,0]
	v_pk_mul_f32 v[60:61], v[60:61], v[2:3] op_sel_hi:[1,0]
	v_pk_mul_f32 v[62:63], v[62:63], v[2:3] op_sel_hi:[1,0]
	v_add_u32_e32 v106, 0x8000, v191
	v_mfma_f32_32x32x16_bf16 v[48:63], v[12:15], v[8:11], v[48:63]
	ds_read2_b64 v[12:15], v106 offset0:224 offset1:226
	v_pk_mul_f32 v[32:33], v[32:33], v[2:3] op_sel_hi:[1,0]
	v_pk_mul_f32 v[34:35], v[34:35], v[2:3] op_sel_hi:[1,0]
	v_pk_mul_f32 v[36:37], v[36:37], v[2:3] op_sel_hi:[1,0]
	v_pk_mul_f32 v[38:39], v[38:39], v[2:3] op_sel_hi:[1,0]
	v_pk_mul_f32 v[40:41], v[40:41], v[2:3] op_sel_hi:[1,0]
	v_pk_mul_f32 v[42:43], v[42:43], v[2:3] op_sel_hi:[1,0]
	v_pk_mul_f32 v[44:45], v[44:45], v[2:3] op_sel_hi:[1,0]
	v_pk_mul_f32 v[46:47], v[46:47], v[2:3] op_sel_hi:[1,0]
	v_pk_mul_f32 v[16:17], v[16:17], v[2:3] op_sel_hi:[1,0]
	v_pk_mul_f32 v[18:19], v[18:19], v[2:3] op_sel_hi:[1,0]
	v_pk_mul_f32 v[20:21], v[20:21], v[2:3] op_sel_hi:[1,0]
	s_waitcnt lgkmcnt(1)
	v_mfma_f32_32x32x16_bf16 v[32:47], v[4:7], v[8:11], v[32:47]
	ds_read2_b64 v[4:7], v104 offset0:132 offset1:134
	v_pk_mul_f32 v[22:23], v[22:23], v[2:3] op_sel_hi:[1,0]
	v_pk_mul_f32 v[24:25], v[24:25], v[2:3] op_sel_hi:[1,0]
	v_pk_mul_f32 v[26:27], v[26:27], v[2:3] op_sel_hi:[1,0]
	v_pk_mul_f32 v[28:29], v[28:29], v[2:3] op_sel_hi:[1,0]
	v_pk_mul_f32 v[30:31], v[30:31], v[2:3] op_sel_hi:[1,0]
	v_mov_b32_e32 v192, v0
	s_waitcnt lgkmcnt(1)
	v_mfma_f32_32x32x16_bf16 v[16:31], v[12:15], v[8:11], v[16:31]
	v_sub_f32 v8, v111, v0
	v_cvt_pk_bf16_f32 v9, v99, v100
	v_exp_f32_e32 v107, v8
	v_cvt_pk_bf16_f32 v8, v97, v98
	v_cvt_pk_bf16_f32 v10, v101, v102
	ds_read2_b64 v[12:15], v3 offset0:164 offset1:166
	v_cvt_pk_bf16_f32 v11, v103, v107
	s_waitcnt lgkmcnt(1)
	s_nop 0
	v_mfma_f32_32x32x16_bf16 v[64:79], v[4:7], v[8:11], v[64:79]
	v_add_f32 v4, v96, v97
	s_nop 0
	v_add_f32 v4, v4, v98
	s_nop 0
	v_add_f32 v4, v4, v99
	s_nop 0
	v_add_f32 v96, v4, v100
	v_sub_f32 v4, v80, v0
	s_waitcnt lgkmcnt(0)
	v_mfma_f32_32x32x16_bf16 v[48:63], v[12:15], v[8:11], v[48:63]
	v_exp_f32_e32 v80, v4
	ds_read2_b64 v[4:7], v105 offset0:196 offset1:198
	v_sub_f32 v12, v81, v0
	s_nop 0
	v_exp_f32_e32 v81, v12
	v_sub_f32 v12, v82, v0
	s_nop 0
	v_exp_f32_e32 v82, v12
	v_sub_f32 v12, v83, v0
	s_waitcnt lgkmcnt(0)
	v_mfma_f32_32x32x16_bf16 v[32:47], v[4:7], v[8:11], v[32:47]
	v_exp_f32_e32 v83, v12
	ds_read2_b64 v[12:15], v106 offset0:228 offset1:230
	v_sub_f32 v4, v84, v0
	s_nop 0
	v_exp_f32_e32 v84, v4
	v_sub_f32 v4, v85, v0
	s_nop 0
	v_exp_f32_e32 v85, v4
	v_sub_f32 v4, v86, v0
	s_waitcnt lgkmcnt(0)
	v_mfma_f32_32x32x16_bf16 v[16:31], v[12:15], v[8:11], v[16:31]
	v_exp_f32_e32 v86, v4
	ds_read2_b64 v[4:7], v104 offset0:136 offset1:138
	v_sub_f32 v8, v87, v0
	ds_read2_b64 v[12:15], v3 offset0:168 offset1:170
	v_exp_f32_e32 v87, v8
	v_cvt_pk_bf16_f32 v8, v80, v81
	v_cvt_pk_bf16_f32 v9, v82, v83
	v_cvt_pk_bf16_f32 v10, v84, v85
	v_cvt_pk_bf16_f32 v11, v86, v87
	s_waitcnt lgkmcnt(1)
	s_nop 0
	v_mfma_f32_32x32x16_bf16 v[64:79], v[4:7], v[8:11], v[64:79]
	v_add_f32 v4, v96, v101
	s_nop 0
	v_add_f32 v4, v4, v102
	s_nop 0
	v_add_f32 v4, v4, v103
	s_nop 0
	v_add_f32 v96, v4, v107
	v_sub_f32 v4, v88, v0
	s_waitcnt lgkmcnt(0)
	v_mfma_f32_32x32x16_bf16 v[48:63], v[12:15], v[8:11], v[48:63]
	v_exp_f32_e32 v88, v4
	ds_read2_b64 v[4:7], v105 offset0:200 offset1:202
	v_sub_f32 v12, v89, v0
	s_nop 0
	v_exp_f32_e32 v89, v12
	v_sub_f32 v12, v90, v0
	s_nop 0
	v_exp_f32_e32 v90, v12
	v_sub_f32 v12, v91, v0
	s_waitcnt lgkmcnt(0)
	v_mfma_f32_32x32x16_bf16 v[32:47], v[4:7], v[8:11], v[32:47]
	v_exp_f32_e32 v91, v12
	ds_read2_b64 v[12:15], v106 offset0:232 offset1:234
	v_sub_f32 v4, v92, v0
	s_nop 0
	v_exp_f32_e32 v92, v4
	v_sub_f32 v4, v93, v0
	s_nop 0
	v_exp_f32_e32 v93, v4
	v_sub_f32 v4, v94, v0
	s_waitcnt lgkmcnt(0)
	v_mfma_f32_32x32x16_bf16 v[16:31], v[12:15], v[8:11], v[16:31]
	v_exp_f32_e32 v94, v4
	ds_read2_b64 v[4:7], v104 offset0:140 offset1:142
	ds_read2_b64 v[12:15], v3 offset0:172 offset1:174
	v_sub_f32 v8, v95, v0
	v_cvt_pk_bf16_f32 v9, v90, v91
	v_exp_f32_e32 v95, v8
	v_cvt_pk_bf16_f32 v8, v88, v89
	v_cvt_pk_bf16_f32 v10, v92, v93
	v_add_f32 v3, v96, v80
	v_cvt_pk_bf16_f32 v11, v94, v95
	v_add_f32 v3, v3, v81
	s_nop 0
	v_add_f32 v3, v3, v82
	s_waitcnt lgkmcnt(1)
	v_mfma_f32_32x32x16_bf16 v[64:79], v[4:7], v[8:11], v[64:79]
	ds_read2_b64 v[4:7], v105 offset0:204 offset1:206
	v_add_f32 v3, v3, v83
	s_nop 0
	v_add_f32 v3, v3, v84
	s_nop 0
	v_add_f32 v3, v3, v85
	s_waitcnt lgkmcnt(1)
	v_mfma_f32_32x32x16_bf16 v[48:63], v[12:15], v[8:11], v[48:63]
	ds_read2_b64 v[12:15], v106 offset0:236 offset1:238
	v_add_f32 v3, v3, v86
	s_nop 0
	v_add_f32 v3, v3, v87
	s_nop 0
	v_add_f32 v3, v3, v88
	s_nop 0
	v_add_f32 v3, v3, v89
	s_waitcnt lgkmcnt(1)
	v_mfma_f32_32x32x16_bf16 v[32:47], v[4:7], v[8:11], v[32:47]
	v_add_f32 v3, v3, v90
	s_nop 0
	v_add_f32 v3, v3, v91
	s_nop 0
	v_add_f32 v3, v3, v92
	s_nop 0
	v_add_f32 v3, v3, v93
	s_waitcnt lgkmcnt(0)
	v_mfma_f32_32x32x16_bf16 v[16:31], v[12:15], v[8:11], v[16:31]
	v_add_f32 v3, v3, v94
	s_nop 0
	v_add_f32 v3, v3, v95
	s_nop 0
	v_fmac_f32_e32 v3, v184, v2
	v_mov_b32_e32 v184, v3
	s_branch .LBB0_587

.LBB0_1215:
	s_and_saveexec_b64 s[70:71], s[8:9]
	s_cbranch_execz .LBB0_1202
	ds_read_b128 v[220:223], v245
	ds_read_b128 v[224:227], v245 offset:32
	ds_read_b128 v[2:5], v245 offset:64
	ds_read_b128 v[6:9], v245 offset:96
	s_waitcnt lgkmcnt(3)
	v_mfma_f32_32x32x16_bf16 v[96:111], v[220:223], v[172:175], 0
	ds_read_b128 v[220:223], v245 offset:128
	s_waitcnt lgkmcnt(3)
	v_mfma_f32_32x32x16_bf16 v[96:111], v[224:227], v[168:171], v[96:111]
	ds_read_b128 v[224:227], v245 offset:160
	s_waitcnt lgkmcnt(3)
	v_mfma_f32_32x32x16_bf16 v[96:111], v[2:5], v[164:167], v[96:111]
	ds_read_b128 v[2:5], v245 offset:192
	s_waitcnt lgkmcnt(3)
	v_mfma_f32_32x32x16_bf16 v[96:111], v[6:9], v[160:163], v[96:111]
	ds_read_b128 v[6:9], v245 offset:224
	s_waitcnt lgkmcnt(3)
	v_mfma_f32_32x32x16_bf16 v[96:111], v[220:223], v[156:159], v[96:111]
	ds_read_b128 v[220:223], v245 offset:256
	s_waitcnt lgkmcnt(3)
	v_mfma_f32_32x32x16_bf16 v[96:111], v[224:227], v[152:155], v[96:111]
	ds_read_b128 v[224:227], v245 offset:288
	s_waitcnt lgkmcnt(3)
	v_mfma_f32_32x32x16_bf16 v[96:111], v[2:5], v[148:151], v[96:111]
	ds_read_b128 v[2:5], v245 offset:320
	s_waitcnt lgkmcnt(3)
	v_mfma_f32_32x32x16_bf16 v[96:111], v[6:9], v[144:147], v[96:111]
	ds_read_b128 v[6:9], v245 offset:352
	s_waitcnt lgkmcnt(3)
	v_mfma_f32_32x32x16_bf16 v[96:111], v[220:223], v[140:143], v[96:111]
	ds_read_b128 v[220:223], v245 offset:384
	s_waitcnt lgkmcnt(3)
	v_mfma_f32_32x32x16_bf16 v[96:111], v[224:227], v[136:139], v[96:111]
	ds_read_b128 v[224:227], v245 offset:416
	s_waitcnt lgkmcnt(3)
	v_mfma_f32_32x32x16_bf16 v[96:111], v[2:5], v[132:135], v[96:111]
	ds_read_b128 v[2:5], v245 offset:448
	s_waitcnt lgkmcnt(3)
	v_mfma_f32_32x32x16_bf16 v[96:111], v[6:9], v[128:131], v[96:111]
	ds_read_b128 v[6:9], v245 offset:480
	s_waitcnt lgkmcnt(3)
	v_mfma_f32_32x32x16_bf16 v[96:111], v[220:223], v[124:127], v[96:111]
	ds_read_b128 v[220:223], v245 offset:16896
	s_waitcnt lgkmcnt(3)
	v_mfma_f32_32x32x16_bf16 v[96:111], v[224:227], v[120:123], v[96:111]
	ds_read_b128 v[224:227], v245 offset:16928
	s_waitcnt lgkmcnt(3)
	v_mfma_f32_32x32x16_bf16 v[96:111], v[2:5], v[116:119], v[96:111]
	ds_read_b128 v[2:5], v245 offset:16960
	s_waitcnt lgkmcnt(3)
	v_mfma_f32_32x32x16_bf16 v[96:111], v[6:9], v[112:115], v[96:111]
	ds_read_b128 v[6:9], v245 offset:16992
	s_waitcnt lgkmcnt(3)
	v_mfma_f32_32x32x16_bf16 v[80:95], v[220:223], v[172:175], 0
	ds_read_b128 v[220:223], v245 offset:17024
	s_waitcnt lgkmcnt(3)
	v_mfma_f32_32x32x16_bf16 v[80:95], v[224:227], v[168:171], v[80:95]
	ds_read_b128 v[224:227], v245 offset:17056
	s_waitcnt lgkmcnt(3)
	v_mfma_f32_32x32x16_bf16 v[80:95], v[2:5], v[164:167], v[80:95]
	ds_read_b128 v[2:5], v245 offset:17088
	s_waitcnt lgkmcnt(3)
	v_mfma_f32_32x32x16_bf16 v[80:95], v[6:9], v[160:163], v[80:95]
	ds_read_b128 v[6:9], v245 offset:17120
	s_waitcnt lgkmcnt(3)
	v_mfma_f32_32x32x16_bf16 v[80:95], v[220:223], v[156:159], v[80:95]
	ds_read_b128 v[220:223], v245 offset:17152
	s_waitcnt lgkmcnt(3)
	v_mfma_f32_32x32x16_bf16 v[80:95], v[224:227], v[152:155], v[80:95]
	ds_read_b128 v[224:227], v245 offset:17184
	s_waitcnt lgkmcnt(3)
	v_mfma_f32_32x32x16_bf16 v[80:95], v[2:5], v[148:151], v[80:95]
	ds_read_b128 v[2:5], v245 offset:17216
	s_waitcnt lgkmcnt(3)
	v_mfma_f32_32x32x16_bf16 v[80:95], v[6:9], v[144:147], v[80:95]
	ds_read_b128 v[6:9], v245 offset:17248
	s_waitcnt lgkmcnt(3)
	v_mfma_f32_32x32x16_bf16 v[80:95], v[220:223], v[140:143], v[80:95]
	ds_read_b128 v[220:223], v245 offset:17280
	s_waitcnt lgkmcnt(3)
	v_mfma_f32_32x32x16_bf16 v[80:95], v[224:227], v[136:139], v[80:95]
	ds_read_b128 v[224:227], v245 offset:17312
	s_waitcnt lgkmcnt(3)
	v_mfma_f32_32x32x16_bf16 v[80:95], v[2:5], v[132:135], v[80:95]
	ds_read_b128 v[2:5], v245 offset:17344
	s_waitcnt lgkmcnt(3)
	v_mfma_f32_32x32x16_bf16 v[80:95], v[6:9], v[128:131], v[80:95]
	ds_read_b128 v[6:9], v245 offset:17376
	s_waitcnt lgkmcnt(3)
	v_mfma_f32_32x32x16_bf16 v[80:95], v[220:223], v[124:127], v[80:95]
	s_waitcnt lgkmcnt(2)
	v_mfma_f32_32x32x16_bf16 v[80:95], v[224:227], v[120:123], v[80:95]
	s_waitcnt lgkmcnt(1)
	v_mfma_f32_32x32x16_bf16 v[80:95], v[2:5], v[116:119], v[80:95]
	s_waitcnt lgkmcnt(0)
	v_mfma_f32_32x32x16_bf16 v[80:95], v[6:9], v[112:115], v[80:95]
	v_max_f32_e32 v0, v97, v97
	v_max_f32_e32 v10, v96, v96
	v_max_f32_e32 v0, v10, v0
	v_max3_f32 v0, v0, v98, v99
	v_max3_f32 v0, v0, v100, v101
	v_max3_f32 v0, v0, v102, v103
	v_max3_f32 v0, v0, v104, v105
	v_max3_f32 v0, v0, v106, v107
	v_max3_f32 v0, v0, v108, v109
	v_max3_f32 v0, v0, v110, v111
	v_and_b32_e32 v3, 64, v218
	v_xor_b32_e32 v2, 32, v218
	v_add_u32_e32 v3, 64, v3
	v_cmp_lt_i32_e32 vcc, v2, v3
	s_nop 1
	v_cndmask_b32_e32 v2, v218, v2, vcc
	v_lshlrev_b32_e32 v2, 2, v2
	s_nop 10
	v_max3_f32 v0, v0, v80, v81
	v_max3_f32 v0, v0, v82, v83
	v_max3_f32 v0, v0, v84, v85
	v_max3_f32 v0, v0, v86, v87
	v_max3_f32 v0, v0, v88, v89
	v_max3_f32 v0, v0, v90, v91
	v_max3_f32 v0, v0, v92, v93
	v_max3_f32 v0, v0, v94, v95
	ds_bpermute_b32 v2, v2, v0
	s_waitcnt lgkmcnt(0)
	v_max3_f32 v0, v236, v0, v2
	v_sub_f32 v4, v97, v0
	v_sub_f32 v3, v96, v0
	v_sub_f32 v5, v100, v0
	v_sub_f32_e32 v2, v236, v0
	v_exp_f32_e32 v8, v4
	v_sub_f32 v4, v98, v0
	v_exp_f32_e32 v3, v3
	v_exp_f32_e32 v9, v4
	v_sub_f32 v4, v99, v0
	v_exp_f32_e32 v11, v5
	v_exp_f32_e32 v10, v4
	v_add_f32 v4, v1, v3
	v_sub_f32 v5, v101, v0
	v_exp_f32_e32 v2, v2
	v_add_f32 v4, v4, v8
	v_exp_f32_e32 v12, v5
	v_add_f32 v4, v4, v9
	v_sub_f32 v5, v102, v0
	v_cvt_pk_bf16_f32 v8, v3, v8
	v_add_f32 v4, v4, v10
	v_exp_f32_e32 v13, v5
	v_add_f32 v4, v4, v11
	v_sub_f32 v5, v103, v0
	v_add_u32_e32 v3, 0x9000, v219
	v_add_f32 v4, v4, v12
	v_exp_f32_e32 v14, v5
	v_add_f32 v4, v4, v13
	v_cvt_pk_bf16_f32 v9, v9, v10
	v_add_f32 v96, v4, v14
	v_sub_f32 v4, v104, v0
	v_add_u32_e32 v104, 0x8000, v219
	v_exp_f32_e32 v97, v4
	v_sub_f32 v4, v105, v0
	v_cvt_pk_bf16_f32 v10, v11, v12
	v_exp_f32_e32 v98, v4
	v_sub_f32 v4, v106, v0
	v_cvt_pk_bf16_f32 v11, v13, v14
	v_exp_f32_e32 v99, v4
	v_sub_f32 v4, v107, v0
	ds_read2_b64 v[12:15], v3 offset0:160 offset1:162
	v_exp_f32_e32 v100, v4
	v_sub_f32 v4, v108, v0
	v_pk_mul_f32 v[64:65], v[64:65], v[2:3] op_sel_hi:[1,0]
	v_pk_mul_f32 v[66:67], v[66:67], v[2:3] op_sel_hi:[1,0]
	v_pk_mul_f32 v[68:69], v[68:69], v[2:3] op_sel_hi:[1,0]
	s_nop 0
	v_exp_f32_e32 v101, v4
	v_sub_f32 v4, v109, v0
	v_pk_mul_f32 v[70:71], v[70:71], v[2:3] op_sel_hi:[1,0]
	v_pk_mul_f32 v[72:73], v[72:73], v[2:3] op_sel_hi:[1,0]
	s_nop 0
	v_exp_f32_e32 v102, v4
	v_sub_f32 v4, v110, v0
	v_pk_mul_f32 v[74:75], v[74:75], v[2:3] op_sel_hi:[1,0]
	v_pk_mul_f32 v[76:77], v[76:77], v[2:3] op_sel_hi:[1,0]
	v_pk_mul_f32 v[78:79], v[78:79], v[2:3] op_sel_hi:[1,0]
	s_nop 0
	v_exp_f32_e32 v103, v4
	ds_read2_b64 v[4:7], v104 offset0:128 offset1:130
	v_add_u32_e32 v105, 0xa000, v219
	s_waitcnt lgkmcnt(0)
	v_mfma_f32_32x32x16_bf16 v[64:79], v[4:7], v[8:11], v[64:79]
	ds_read2_b64 v[4:7], v105 offset0:192 offset1:194
	v_pk_mul_f32 v[48:49], v[48:49], v[2:3] op_sel_hi:[1,0]
	v_pk_mul_f32 v[50:51], v[50:51], v[2:3] op_sel_hi:[1,0]
	v_pk_mul_f32 v[52:53], v[52:53], v[2:3] op_sel_hi:[1,0]
	v_pk_mul_f32 v[54:55], v[54:55], v[2:3] op_sel_hi:[1,0]
	v_pk_mul_f32 v[56:57], v[56:57], v[2:3] op_sel_hi:[1,0]
	v_pk_mul_f32 v[58:59], v[58:59], v[2:3] op_sel_hi:[1,0]
	v_pk_mul_f32 v[60:61], v[60:61], v[2:3] op_sel_hi:[1,0]
	v_pk_mul_f32 v[62:63], v[62:63], v[2:3] op_sel_hi:[1,0]
	v_add_u32_e32 v106, 0xb000, v219
	v_mfma_f32_32x32x16_bf16 v[48:63], v[12:15], v[8:11], v[48:63]
	ds_read2_b64 v[12:15], v106 offset0:224 offset1:226
	v_pk_mul_f32 v[32:33], v[32:33], v[2:3] op_sel_hi:[1,0]
	v_pk_mul_f32 v[34:35], v[34:35], v[2:3] op_sel_hi:[1,0]
	v_pk_mul_f32 v[36:37], v[36:37], v[2:3] op_sel_hi:[1,0]
	v_pk_mul_f32 v[38:39], v[38:39], v[2:3] op_sel_hi:[1,0]
	v_pk_mul_f32 v[40:41], v[40:41], v[2:3] op_sel_hi:[1,0]
	v_pk_mul_f32 v[42:43], v[42:43], v[2:3] op_sel_hi:[1,0]
	v_pk_mul_f32 v[44:45], v[44:45], v[2:3] op_sel_hi:[1,0]
	v_pk_mul_f32 v[46:47], v[46:47], v[2:3] op_sel_hi:[1,0]
	v_pk_mul_f32 v[16:17], v[16:17], v[2:3] op_sel_hi:[1,0]
	v_pk_mul_f32 v[18:19], v[18:19], v[2:3] op_sel_hi:[1,0]
	v_pk_mul_f32 v[20:21], v[20:21], v[2:3] op_sel_hi:[1,0]
	s_waitcnt lgkmcnt(1)
	v_mfma_f32_32x32x16_bf16 v[32:47], v[4:7], v[8:11], v[32:47]
	ds_read2_b64 v[4:7], v104 offset0:132 offset1:134
	v_pk_mul_f32 v[22:23], v[22:23], v[2:3] op_sel_hi:[1,0]
	v_pk_mul_f32 v[24:25], v[24:25], v[2:3] op_sel_hi:[1,0]
	v_pk_mul_f32 v[26:27], v[26:27], v[2:3] op_sel_hi:[1,0]
	v_pk_mul_f32 v[28:29], v[28:29], v[2:3] op_sel_hi:[1,0]
	v_pk_mul_f32 v[30:31], v[30:31], v[2:3] op_sel_hi:[1,0]
	v_mov_b32_e32 v236, v0
	s_waitcnt lgkmcnt(1)
	v_mfma_f32_32x32x16_bf16 v[16:31], v[12:15], v[8:11], v[16:31]
	v_sub_f32 v8, v111, v0
	v_cvt_pk_bf16_f32 v9, v99, v100
	v_exp_f32_e32 v107, v8
	v_cvt_pk_bf16_f32 v8, v97, v98
	v_cvt_pk_bf16_f32 v10, v101, v102
	ds_read2_b64 v[12:15], v3 offset0:164 offset1:166
	v_cvt_pk_bf16_f32 v11, v103, v107
	s_waitcnt lgkmcnt(1)
	s_nop 0
	v_mfma_f32_32x32x16_bf16 v[64:79], v[4:7], v[8:11], v[64:79]
	v_add_f32 v4, v96, v97
	s_nop 0
	v_add_f32 v4, v4, v98
	s_nop 0
	v_add_f32 v4, v4, v99
	s_nop 0
	v_add_f32 v96, v4, v100
	v_sub_f32 v4, v80, v0
	s_waitcnt lgkmcnt(0)
	v_mfma_f32_32x32x16_bf16 v[48:63], v[12:15], v[8:11], v[48:63]
	v_exp_f32_e32 v80, v4
	ds_read2_b64 v[4:7], v105 offset0:196 offset1:198
	v_sub_f32 v12, v81, v0
	s_nop 0
	v_exp_f32_e32 v81, v12
	v_sub_f32 v12, v82, v0
	s_nop 0
	v_exp_f32_e32 v82, v12
	v_sub_f32 v12, v83, v0
	s_waitcnt lgkmcnt(0)
	v_mfma_f32_32x32x16_bf16 v[32:47], v[4:7], v[8:11], v[32:47]
	v_exp_f32_e32 v83, v12
	ds_read2_b64 v[12:15], v106 offset0:228 offset1:230
	v_sub_f32 v4, v84, v0
	s_nop 0
	v_exp_f32_e32 v84, v4
	v_sub_f32 v4, v85, v0
	s_nop 0
	v_exp_f32_e32 v85, v4
	v_sub_f32 v4, v86, v0
	s_waitcnt lgkmcnt(0)
	v_mfma_f32_32x32x16_bf16 v[16:31], v[12:15], v[8:11], v[16:31]
	v_exp_f32_e32 v86, v4
	ds_read2_b64 v[4:7], v104 offset0:136 offset1:138
	v_sub_f32 v8, v87, v0
	ds_read2_b64 v[12:15], v3 offset0:168 offset1:170
	v_exp_f32_e32 v87, v8
	v_cvt_pk_bf16_f32 v8, v80, v81
	v_cvt_pk_bf16_f32 v9, v82, v83
	v_cvt_pk_bf16_f32 v10, v84, v85
	v_cvt_pk_bf16_f32 v11, v86, v87
	s_waitcnt lgkmcnt(1)
	s_nop 0
	v_mfma_f32_32x32x16_bf16 v[64:79], v[4:7], v[8:11], v[64:79]
	v_add_f32 v4, v96, v101
	s_nop 0
	v_add_f32 v4, v4, v102
	s_nop 0
	v_add_f32 v4, v4, v103
	s_nop 0
	v_add_f32 v96, v4, v107
	v_sub_f32 v4, v88, v0
	s_waitcnt lgkmcnt(0)
	v_mfma_f32_32x32x16_bf16 v[48:63], v[12:15], v[8:11], v[48:63]
	v_exp_f32_e32 v88, v4
	ds_read2_b64 v[4:7], v105 offset0:200 offset1:202
	v_sub_f32 v12, v89, v0
	s_nop 0
	v_exp_f32_e32 v89, v12
	v_sub_f32 v12, v90, v0
	s_nop 0
	v_exp_f32_e32 v90, v12
	v_sub_f32 v12, v91, v0
	s_waitcnt lgkmcnt(0)
	v_mfma_f32_32x32x16_bf16 v[32:47], v[4:7], v[8:11], v[32:47]
	v_exp_f32_e32 v91, v12
	ds_read2_b64 v[12:15], v106 offset0:232 offset1:234
	v_sub_f32 v4, v92, v0
	s_nop 0
	v_exp_f32_e32 v92, v4
	v_sub_f32 v4, v93, v0
	s_nop 0
	v_exp_f32_e32 v93, v4
	v_sub_f32 v4, v94, v0
	s_waitcnt lgkmcnt(0)
	v_mfma_f32_32x32x16_bf16 v[16:31], v[12:15], v[8:11], v[16:31]
	v_exp_f32_e32 v94, v4
	ds_read2_b64 v[4:7], v104 offset0:140 offset1:142
	ds_read2_b64 v[12:15], v3 offset0:172 offset1:174
	v_sub_f32 v8, v95, v0
	v_cvt_pk_bf16_f32 v9, v90, v91
	v_exp_f32_e32 v95, v8
	v_cvt_pk_bf16_f32 v8, v88, v89
	v_cvt_pk_bf16_f32 v10, v92, v93
	v_add_f32 v3, v96, v80
	v_cvt_pk_bf16_f32 v11, v94, v95
	v_add_f32 v3, v3, v81
	s_nop 0
	v_add_f32 v3, v3, v82
	s_waitcnt lgkmcnt(1)
	v_mfma_f32_32x32x16_bf16 v[64:79], v[4:7], v[8:11], v[64:79]
	ds_read2_b64 v[4:7], v105 offset0:204 offset1:206
	v_add_f32 v3, v3, v83
	s_nop 0
	v_add_f32 v3, v3, v84
	s_nop 0
	v_add_f32 v3, v3, v85
	s_waitcnt lgkmcnt(1)
	v_mfma_f32_32x32x16_bf16 v[48:63], v[12:15], v[8:11], v[48:63]
	ds_read2_b64 v[12:15], v106 offset0:236 offset1:238
	v_add_f32 v3, v3, v86
	s_nop 0
	v_add_f32 v3, v3, v87
	s_nop 0
	v_add_f32 v3, v3, v88
	s_nop 0
	v_add_f32 v3, v3, v89
	s_waitcnt lgkmcnt(1)
	v_mfma_f32_32x32x16_bf16 v[32:47], v[4:7], v[8:11], v[32:47]
	v_add_f32 v3, v3, v90
	s_nop 0
	v_add_f32 v3, v3, v91
	s_nop 0
	v_add_f32 v3, v3, v92
	s_nop 0
	v_add_f32 v3, v3, v93
	s_waitcnt lgkmcnt(0)
	v_mfma_f32_32x32x16_bf16 v[16:31], v[12:15], v[8:11], v[16:31]
	v_add_f32 v3, v3, v94
	s_nop 0
	v_add_f32 v3, v3, v95
	s_nop 0
	v_fmac_f32_e32 v3, v246, v2
	v_mov_b32_e32 v246, v3
	s_branch .LBB0_1202
